# phase0 weight conversion rewritten by hand: LDS-DMA staging, 3 tiles in flight, flattened job groups
# speedup vs baseline: 1.0041x; 1.0041x over previous
; __device__ __forceinline__ int opaque_tid() { int t = threadIdx.x; asm volatile("" : "+v"(t)); return t; }
; #define CVT_LOAD(tile_) do { const int k0_ = ((tile_) / ntn) << 7, n0_ = ((tile_) % ntn) << 6; \
;         _Pragma("unroll") for (int pp = 0; pp < 4; ++pp) pv[pp] = *(const float4*)(src + (size_t)(k0_ + lk + 32 * pp) * N + n0_ + ln4); } while (0)
; __device__ __forceinline__ void convT_job(const float* __restrict__ src, bf16_t* __restrict__ dst, int K, int N, int mode, float* t) {
;     const int tid = opaque_tid(), ntn = N >> 6, ntiles = (K >> 7) * ntn;
;     const int lk = tid >> 4, ln4 = (tid & 15) * 4;
;     float4 pv[4];
;     ...
;     int tile = blockIdx.x;
;     if (tile < ntiles) CVT_LOAD(tile);
; __device__ __forceinline__ void phase_convert(const Params& p, unsigned char* smem) {
;     float* t = (float*)smem;
;     for (int l = 0; l < 2; ++l) {
;         for (int f = 0; f < 2; ++f) {
;             const size_t wo = (size_t)(l * 2 + f) * 2048 * 5632;
;             bf16_t* gu = (bf16_t*)(p.ws + OFF_GU + (size_t)(l * 2 + f) * SZ_GU);
;             convT_job(p.in[3] + wo, gu, 2048, 5632, 1, t);
.LBB0_623:
	v_lshrrev_b32_e32 v6, 6, v234
	v_and_b32_e32 v25, 63, v234
	v_lshrrev_b32_e32 v26, 3, v234
	v_readfirstlane_b32 s46, v6
	v_and_b32_e32 v27, 7, v234
	v_readlane_b32 s54, v255, 28
	v_readlane_b32 s55, v255, 29
	s_lshl_b32 s46, s46, 12
	v_lshrrev_b32_e32 v28, 2, v26
	v_xor_b32_e32 v28, v28, v27
	v_lshlrev_b32_e32 v28, 4, v28
	v_and_b32_e32 v29, 3, v26
	v_lshl_or_b32 v28, v29, 2, v28
	v_lshl_or_b32 v4, v27, 12, v28
	v_lshrrev_b32_e32 v30, 4, v25
	v_lshl_add_u32 v30, v6, 4, v30
	v_and_b32_e32 v31, 15, v25
	v_xor_b32_e32 v31, v31, v6
	v_lshlrev_b32_e32 v31, 4, v31
	v_lshlrev_b32_e32 v27, 5, v27
	s_mov_b32 s40, s60
	s_cmp_lt_u32 s40, 5632
	s_cbranch_scc0 .Lcv_gate_skip
	v_mov_b32_e32 v29, 0x5800
	v_mov_b32_e32 v28, 0x1000
	v_mad_u32_u24 v0, v30, v29, v31
	v_mad_u32_u24 v5, v26, v28, v27
	v_add_u32_e32 v1, 0x16000, v0
	v_add_u32_e32 v2, 0x2c000, v0
	v_add_u32_e32 v3, 0x42000, v0
	s_barrier
	s_mov_b32 s41, 0
	s_mov_b32 s47, s40
	s_mov_b32 s48, s46
	s_mul_hi_u32 s0, s47, 0x2e8ba3
	s_mul_i32 s1, s0, 1408
	s_sub_u32 s1, s47, s1
	s_mul_hi_u32 s2, s1, 0x2e8ba2f
	s_mul_i32 s8, s2, 88
	s_sub_u32 s8, s1, s8
	s_mul_i32 s9, s0, 0x2c00000
	s_mul_i32 s28, s2, 0x2c0000
	s_add_u32 s9, s9, s28
	s_lshl_b32 s8, s8, 8
	s_add_u32 s9, s9, s8
	s_add_u32 s42, s70, s9
	s_addc_u32 s43, s71, 0
	s_mov_b32 m0, s48
	s_add_u32 s49, s48, 0x400
	global_load_lds_dwordx4 v0, s[42:43]
	s_mov_b32 m0, s49
	s_add_u32 s49, s48, 0x800
	global_load_lds_dwordx4 v1, s[42:43]
	s_mov_b32 m0, s49
	s_add_u32 s49, s48, 0xc00
	global_load_lds_dwordx4 v2, s[42:43]
	s_mov_b32 m0, s49
	s_nop 0
	global_load_lds_dwordx4 v3, s[42:43]
	global_load_dword v24, v173, s[70:71]
	global_load_dword v24, v173, s[70:71]
	s_add_u32 s47, s40, 256
	s_add_u32 s48, s46, 0x8000
	s_cmp_lt_u32 s47, 5632
	s_cbranch_scc0 .Lcv_gate_pd1
	s_mul_hi_u32 s0, s47, 0x2e8ba3
	s_mul_i32 s1, s0, 1408
	s_sub_u32 s1, s47, s1
	s_mul_hi_u32 s2, s1, 0x2e8ba2f
	s_mul_i32 s8, s2, 88
	s_sub_u32 s8, s1, s8
	s_mul_i32 s9, s0, 0x2c00000
	s_mul_i32 s28, s2, 0x2c0000
	s_add_u32 s9, s9, s28
	s_lshl_b32 s8, s8, 8
	s_add_u32 s9, s9, s8
	s_add_u32 s42, s70, s9
	s_addc_u32 s43, s71, 0
	s_mov_b32 m0, s48
	s_add_u32 s49, s48, 0x400
	global_load_lds_dwordx4 v0, s[42:43]
	s_mov_b32 m0, s49
	s_add_u32 s49, s48, 0x800
	global_load_lds_dwordx4 v1, s[42:43]
	s_mov_b32 m0, s49
	s_add_u32 s49, s48, 0xc00
	global_load_lds_dwordx4 v2, s[42:43]
	s_mov_b32 m0, s49
	s_nop 0
	global_load_lds_dwordx4 v3, s[42:43]
	s_branch .Lcv_gate_pj1
.Lcv_gate_pd1:
	global_load_dword v24, v173, s[70:71]
	global_load_dword v24, v173, s[70:71]
	global_load_dword v24, v173, s[70:71]
	global_load_dword v24, v173, s[70:71]
.Lcv_gate_pj1:
	global_load_dword v24, v173, s[70:71]
	global_load_dword v24, v173, s[70:71]
	s_add_u32 s47, s40, 512
	s_add_u32 s48, s46, 0x10000
	s_cmp_lt_u32 s47, 5632
	s_cbranch_scc0 .Lcv_gate_pd2
	s_mul_hi_u32 s0, s47, 0x2e8ba3
	s_mul_i32 s1, s0, 1408
	s_sub_u32 s1, s47, s1
	s_mul_hi_u32 s2, s1, 0x2e8ba2f
	s_mul_i32 s8, s2, 88
	s_sub_u32 s8, s1, s8
	s_mul_i32 s9, s0, 0x2c00000
	s_mul_i32 s28, s2, 0x2c0000
	s_add_u32 s9, s9, s28
	s_lshl_b32 s8, s8, 8
	s_add_u32 s9, s9, s8
	s_add_u32 s42, s70, s9
	s_addc_u32 s43, s71, 0
	s_mov_b32 m0, s48
	s_add_u32 s49, s48, 0x400
	global_load_lds_dwordx4 v0, s[42:43]
	s_mov_b32 m0, s49
	s_add_u32 s49, s48, 0x800
	global_load_lds_dwordx4 v1, s[42:43]
	s_mov_b32 m0, s49
	s_add_u32 s49, s48, 0xc00
	global_load_lds_dwordx4 v2, s[42:43]
	s_mov_b32 m0, s49
	s_nop 0
	global_load_lds_dwordx4 v3, s[42:43]
	s_branch .Lcv_gate_pj2

; __device__ __forceinline__ void lds_barrier() { asm volatile("s_waitcnt lgkmcnt(0)" ::: "memory"); __builtin_amdgcn_s_barrier(); asm volatile("" ::: "memory"); }
; #define CVT_LOAD(tile_) do { const int k0_ = ((tile_) / ntn) << 7, n0_ = ((tile_) % ntn) << 6; \
;         _Pragma("unroll") for (int pp = 0; pp < 4; ++pp) pv[pp] = *(const float4*)(src + (size_t)(k0_ + lk + 32 * pp) * N + n0_ + ln4); } while (0)
; __device__ __forceinline__ void convT_job(const float* __restrict__ src, bf16_t* __restrict__ dst, int K, int N, int mode, float* t) {
;     ...
; #pragma unroll 1
;     for (; tile < ntiles; tile += gridDim.x) {
;         const int k0 = (tile / ntn) << 7, n0 = (tile % ntn) << 6;
; #pragma unroll
;         for (int pp = 0; pp < 4; ++pp) { const int k = lk + 32 * pp; t[k * 65 + ln4] = pv[pp].x; t[k * 65 + ln4 + 1] = pv[pp].y; t[k * 65 + ln4 + 2] = pv[pp].z; t[k * 65 + ln4 + 3] = pv[pp].w; }
;         if (tile + (int)gridDim.x < ntiles) CVT_LOAD(tile + (int)gridDim.x);
;         lds_barrier();
.Lcv_gate_pj2:
	global_load_dword v24, v173, s[70:71]
	global_load_dword v24, v173, s[70:71]
.Lcv_gate_loop:
	s_waitcnt vmcnt(14)
	s_barrier
	s_add_u32 s47, s40, 768
	s_add_u32 s48, s41, 0x18000
	s_and_b32 s48, s48, 0x1ffff
	s_add_u32 s48, s48, s46
	s_cmp_lt_u32 s47, 5632
	s_cbranch_scc0 .Lcv_gate_ld
	s_mul_hi_u32 s0, s47, 0x2e8ba3
	s_mul_i32 s1, s0, 1408
	s_sub_u32 s1, s47, s1
	s_mul_hi_u32 s2, s1, 0x2e8ba2f
	s_mul_i32 s8, s2, 88
	s_sub_u32 s8, s1, s8
	s_mul_i32 s9, s0, 0x2c00000
	s_mul_i32 s28, s2, 0x2c0000
	s_add_u32 s9, s9, s28
	s_lshl_b32 s8, s8, 8
	s_add_u32 s9, s9, s8
	s_add_u32 s42, s70, s9
	s_addc_u32 s43, s71, 0
	s_mov_b32 m0, s48
	s_add_u32 s49, s48, 0x400
	global_load_lds_dwordx4 v0, s[42:43]
	s_mov_b32 m0, s49
	s_add_u32 s49, s48, 0x800
	global_load_lds_dwordx4 v1, s[42:43]
	s_mov_b32 m0, s49
	s_add_u32 s49, s48, 0xc00
	global_load_lds_dwordx4 v2, s[42:43]
	s_mov_b32 m0, s49
	s_nop 0
	global_load_lds_dwordx4 v3, s[42:43]
	s_branch .Lcv_gate_lj

; __device__ __forceinline__ unsigned cvt_pk_bf16(float lo, float hi) { unsigned r; asm volatile("v_cvt_pk_bf16_f32 %0, %1, %2" : "=v"(r) : "v"(lo), "v"(hi)); return r; }
; __device__ __forceinline__ void lds_barrier() { asm volatile("s_waitcnt lgkmcnt(0)" ::: "memory"); __builtin_amdgcn_s_barrier(); asm volatile("" ::: "memory"); }
; __device__ __forceinline__ void convT_job(const float* __restrict__ src, bf16_t* __restrict__ dst, int K, int N, int mode, float* t) {
;     ...
;         const int n = tid >> 3, k16 = (tid & 7) * 16;
;         float v[16];
; #pragma unroll
;         for (int j = 0; j < 16; ++j) v[j] = t[(k16 + j) * 65 + n];
;         const int nn = n0 + n;
;         const int row = mode == 0 ? nn : (256 * (nn >> 7) + (nn & 127) + (mode == 2 ? 128 : 0));
;         u32x4 w0, w1; w0.x = cvt_pk_bf16(v[0], v[1]); w0.y = cvt_pk_bf16(v[2], v[3]); w0.z = cvt_pk_bf16(v[4], v[5]); w0.w = cvt_pk_bf16(v[6], v[7]);
;         w1.x = cvt_pk_bf16(v[8], v[9]); w1.y = cvt_pk_bf16(v[10], v[11]); w1.z = cvt_pk_bf16(v[12], v[13]); w1.w = cvt_pk_bf16(v[14], v[15]);
;         bf16_t* d = dst + (size_t)row * K + k0 + k16;
;         *(u32x4*)d = w0; *(u32x4*)(d + 8) = w1;
;         lds_barrier();
; __device__ __forceinline__ void phase_convert(const Params& p, unsigned char* smem) {
;     ...
;             convT_job(p.in[4] + wo, gu, 2048, 5632, 2, t);
.Lcv_gate_lj:
	v_add_u32_e32 v7, s41, v4
	ds_read2st64_b32 v[8:9], v7 offset0:0 offset1:1
	ds_read2st64_b32 v[10:11], v7 offset0:2 offset1:3
	ds_read2st64_b32 v[12:13], v7 offset0:4 offset1:5
	ds_read2st64_b32 v[14:15], v7 offset0:6 offset1:7
	ds_read2st64_b32 v[16:17], v7 offset0:8 offset1:9
	ds_read2st64_b32 v[18:19], v7 offset0:10 offset1:11
	ds_read2st64_b32 v[20:21], v7 offset0:12 offset1:13
	ds_read2st64_b32 v[22:23], v7 offset0:14 offset1:15
	s_mul_hi_u32 s0, s40, 0x2e8ba3
	s_mul_i32 s1, s0, 1408
	s_sub_u32 s1, s40, s1
	s_mul_hi_u32 s2, s1, 0x2e8ba2f
	s_mul_i32 s8, s2, 88
	s_sub_u32 s8, s1, s8
	s_lshr_b32 s9, s8, 1
	s_lshl_b32 s9, s9, 8
	s_and_b32 s28, s8, 1
	s_lshl_b32 s28, s28, 6
	s_add_u32 s9, s9, s28
	s_mul_i32 s9, s9, 0x1000
	s_mul_i32 s28, s0, 0x2c00000
	s_add_u32 s9, s9, s28
	s_lshl_b32 s2, s2, 8
	s_add_u32 s9, s9, s2
	s_add_u32 s9, s9, 0x8000
	s_add_u32 s44, s54, s9
	s_addc_u32 s45, s55, 0
	s_waitcnt lgkmcnt(6)
	v_cvt_pk_bf16_f32 v8, v8, v9
	v_cvt_pk_bf16_f32 v9, v10, v11
	s_waitcnt lgkmcnt(4)
	v_cvt_pk_bf16_f32 v10, v12, v13
	v_cvt_pk_bf16_f32 v11, v14, v15
	s_waitcnt lgkmcnt(2)
	v_cvt_pk_bf16_f32 v12, v16, v17
	v_cvt_pk_bf16_f32 v13, v18, v19
	s_waitcnt lgkmcnt(0)
	v_cvt_pk_bf16_f32 v14, v20, v21
	v_cvt_pk_bf16_f32 v15, v22, v23
	global_store_dwordx4 v5, v[8:11], s[44:45]
	global_store_dwordx4 v5, v[12:15], s[44:45] offset:16
	s_add_u32 s40, s40, 256
	s_add_u32 s41, s41, 0x8000
	s_and_b32 s41, s41, 0x1ffff
	s_cmp_lt_u32 s40, 5632
	s_cbranch_scc1 .Lcv_gate_loop
.Lcv_gate_skip:
	s_mov_b32 s40, s60
	s_cmp_lt_u32 s40, 5632
	s_cbranch_scc0 .Lcv_up_skip
	v_mov_b32_e32 v29, 0x5800
	v_mov_b32_e32 v28, 0x1000
	v_mad_u32_u24 v0, v30, v29, v31
	v_mad_u32_u24 v5, v26, v28, v27
	v_add_u32_e32 v1, 0x16000, v0
	v_add_u32_e32 v2, 0x2c000, v0
	v_add_u32_e32 v3, 0x42000, v0
	s_barrier
	s_mov_b32 s41, 0
	s_mov_b32 s47, s40
	s_mov_b32 s48, s46
	s_mul_hi_u32 s0, s47, 0x2e8ba3
	s_mul_i32 s1, s0, 1408
	s_sub_u32 s1, s47, s1
	s_mul_hi_u32 s2, s1, 0x2e8ba2f
	s_mul_i32 s8, s2, 88
	s_sub_u32 s8, s1, s8
	s_mul_i32 s9, s0, 0x2c00000
	s_mul_i32 s28, s2, 0x2c0000
	s_add_u32 s9, s9, s28
	s_lshl_b32 s8, s8, 8
	s_add_u32 s9, s9, s8
	s_add_u32 s42, s72, s9
	s_addc_u32 s43, s73, 0
	s_mov_b32 m0, s48
	s_add_u32 s49, s48, 0x400
	global_load_lds_dwordx4 v0, s[42:43]
	s_mov_b32 m0, s49
	s_add_u32 s49, s48, 0x800
	global_load_lds_dwordx4 v1, s[42:43]
	s_mov_b32 m0, s49
	s_add_u32 s49, s48, 0xc00
	global_load_lds_dwordx4 v2, s[42:43]
	s_mov_b32 m0, s49
	s_nop 0
	global_load_lds_dwordx4 v3, s[42:43]
	global_load_dword v24, v173, s[72:73]
	global_load_dword v24, v173, s[72:73]
	s_add_u32 s47, s40, 256
	s_add_u32 s48, s46, 0x8000
	s_cmp_lt_u32 s47, 5632
	s_cbranch_scc0 .Lcv_up_pd1
	s_mul_hi_u32 s0, s47, 0x2e8ba3
	s_mul_i32 s1, s0, 1408
	s_sub_u32 s1, s47, s1
	s_mul_hi_u32 s2, s1, 0x2e8ba2f
	s_mul_i32 s8, s2, 88
	s_sub_u32 s8, s1, s8
	s_mul_i32 s9, s0, 0x2c00000
	s_mul_i32 s28, s2, 0x2c0000
	s_add_u32 s9, s9, s28
	s_lshl_b32 s8, s8, 8
	s_add_u32 s9, s9, s8
	s_add_u32 s42, s72, s9
	s_addc_u32 s43, s73, 0
	s_mov_b32 m0, s48
	s_add_u32 s49, s48, 0x400
	global_load_lds_dwordx4 v0, s[42:43]
	s_mov_b32 m0, s49
	s_add_u32 s49, s48, 0x800
	global_load_lds_dwordx4 v1, s[42:43]
	s_mov_b32 m0, s49
	s_add_u32 s49, s48, 0xc00
	global_load_lds_dwordx4 v2, s[42:43]
	s_mov_b32 m0, s49
	s_nop 0
	global_load_lds_dwordx4 v3, s[42:43]
	s_branch .Lcv_up_pj1
.Lcv_up_pd1:
	global_load_dword v24, v173, s[72:73]
	global_load_dword v24, v173, s[72:73]
	global_load_dword v24, v173, s[72:73]
	global_load_dword v24, v173, s[72:73]
.Lcv_up_pj1:
	global_load_dword v24, v173, s[72:73]
	global_load_dword v24, v173, s[72:73]
	s_add_u32 s47, s40, 512
	s_add_u32 s48, s46, 0x10000
	s_cmp_lt_u32 s47, 5632
	s_cbranch_scc0 .Lcv_up_pd2
	s_mul_hi_u32 s0, s47, 0x2e8ba3
	s_mul_i32 s1, s0, 1408
	s_sub_u32 s1, s47, s1
	s_mul_hi_u32 s2, s1, 0x2e8ba2f
	s_mul_i32 s8, s2, 88
	s_sub_u32 s8, s1, s8
	s_mul_i32 s9, s0, 0x2c00000
	s_mul_i32 s28, s2, 0x2c0000
	s_add_u32 s9, s9, s28
	s_lshl_b32 s8, s8, 8
	s_add_u32 s9, s9, s8
	s_add_u32 s42, s72, s9
	s_addc_u32 s43, s73, 0
	s_mov_b32 m0, s48
	s_add_u32 s49, s48, 0x400
	global_load_lds_dwordx4 v0, s[42:43]
	s_mov_b32 m0, s49
	s_add_u32 s49, s48, 0x800
	global_load_lds_dwordx4 v1, s[42:43]
	s_mov_b32 m0, s49
	s_add_u32 s49, s48, 0xc00
	global_load_lds_dwordx4 v2, s[42:43]
	s_mov_b32 m0, s49
	s_nop 0
	global_load_lds_dwordx4 v3, s[42:43]
	s_branch .Lcv_up_pj2

; __device__ __forceinline__ void lds_barrier() { asm volatile("s_waitcnt lgkmcnt(0)" ::: "memory"); __builtin_amdgcn_s_barrier(); asm volatile("" ::: "memory"); }
; #define CVT_LOAD(tile_) do { const int k0_ = ((tile_) / ntn) << 7, n0_ = ((tile_) % ntn) << 6; \
;         _Pragma("unroll") for (int pp = 0; pp < 4; ++pp) pv[pp] = *(const float4*)(src + (size_t)(k0_ + lk + 32 * pp) * N + n0_ + ln4); } while (0)
; __device__ __forceinline__ void convT_job(const float* __restrict__ src, bf16_t* __restrict__ dst, int K, int N, int mode, float* t) {
;     ...
; #pragma unroll 1
;     for (; tile < ntiles; tile += gridDim.x) {
;         const int k0 = (tile / ntn) << 7, n0 = (tile % ntn) << 6;
; #pragma unroll
;         for (int pp = 0; pp < 4; ++pp) { const int k = lk + 32 * pp; t[k * 65 + ln4] = pv[pp].x; t[k * 65 + ln4 + 1] = pv[pp].y; t[k * 65 + ln4 + 2] = pv[pp].z; t[k * 65 + ln4 + 3] = pv[pp].w; }
;         if (tile + (int)gridDim.x < ntiles) CVT_LOAD(tile + (int)gridDim.x);
;         lds_barrier();
.Lcv_up_pj2:
	global_load_dword v24, v173, s[72:73]
	global_load_dword v24, v173, s[72:73]
.Lcv_up_loop:
	s_waitcnt vmcnt(14)
	s_barrier
	s_add_u32 s47, s40, 768
	s_add_u32 s48, s41, 0x18000
	s_and_b32 s48, s48, 0x1ffff
	s_add_u32 s48, s48, s46
	s_cmp_lt_u32 s47, 5632
	s_cbranch_scc0 .Lcv_up_ld
	s_mul_hi_u32 s0, s47, 0x2e8ba3
	s_mul_i32 s1, s0, 1408
	s_sub_u32 s1, s47, s1
	s_mul_hi_u32 s2, s1, 0x2e8ba2f
	s_mul_i32 s8, s2, 88
	s_sub_u32 s8, s1, s8
	s_mul_i32 s9, s0, 0x2c00000
	s_mul_i32 s28, s2, 0x2c0000
	s_add_u32 s9, s9, s28
	s_lshl_b32 s8, s8, 8
	s_add_u32 s9, s9, s8
	s_add_u32 s42, s72, s9
	s_addc_u32 s43, s73, 0
	s_mov_b32 m0, s48
	s_add_u32 s49, s48, 0x400
	global_load_lds_dwordx4 v0, s[42:43]
	s_mov_b32 m0, s49
	s_add_u32 s49, s48, 0x800
	global_load_lds_dwordx4 v1, s[42:43]
	s_mov_b32 m0, s49
	s_add_u32 s49, s48, 0xc00
	global_load_lds_dwordx4 v2, s[42:43]
	s_mov_b32 m0, s49
	s_nop 0
	global_load_lds_dwordx4 v3, s[42:43]
	s_branch .Lcv_up_lj

; __device__ __forceinline__ unsigned cvt_pk_bf16(float lo, float hi) { unsigned r; asm volatile("v_cvt_pk_bf16_f32 %0, %1, %2" : "=v"(r) : "v"(lo), "v"(hi)); return r; }
; __device__ __forceinline__ void lds_barrier() { asm volatile("s_waitcnt lgkmcnt(0)" ::: "memory"); __builtin_amdgcn_s_barrier(); asm volatile("" ::: "memory"); }
; __device__ __forceinline__ void convT_job(const float* __restrict__ src, bf16_t* __restrict__ dst, int K, int N, int mode, float* t) {
;     ...
;         const int n = tid >> 3, k16 = (tid & 7) * 16;
;         float v[16];
; #pragma unroll
;         for (int j = 0; j < 16; ++j) v[j] = t[(k16 + j) * 65 + n];
;         const int nn = n0 + n;
;         const int row = mode == 0 ? nn : (256 * (nn >> 7) + (nn & 127) + (mode == 2 ? 128 : 0));
;         u32x4 w0, w1; w0.x = cvt_pk_bf16(v[0], v[1]); w0.y = cvt_pk_bf16(v[2], v[3]); w0.z = cvt_pk_bf16(v[4], v[5]); w0.w = cvt_pk_bf16(v[6], v[7]);
;         w1.x = cvt_pk_bf16(v[8], v[9]); w1.y = cvt_pk_bf16(v[10], v[11]); w1.z = cvt_pk_bf16(v[12], v[13]); w1.w = cvt_pk_bf16(v[14], v[15]);
;         bf16_t* d = dst + (size_t)row * K + k0 + k16;
;         *(u32x4*)d = w0; *(u32x4*)(d + 8) = w1;
;         lds_barrier();
; __device__ __forceinline__ void phase_convert(const Params& p, unsigned char* smem) {
;     ...
;             convT_job(p.in[5] + wo, (bf16_t*)(p.ws + OFF_DN + (size_t)(l * 2 + f) * SZ_DN), 5632, 2048, 0, t);
.Lcv_up_lj:
	v_add_u32_e32 v7, s41, v4
	ds_read2st64_b32 v[8:9], v7 offset0:0 offset1:1
	ds_read2st64_b32 v[10:11], v7 offset0:2 offset1:3
	ds_read2st64_b32 v[12:13], v7 offset0:4 offset1:5
	ds_read2st64_b32 v[14:15], v7 offset0:6 offset1:7
	ds_read2st64_b32 v[16:17], v7 offset0:8 offset1:9
	ds_read2st64_b32 v[18:19], v7 offset0:10 offset1:11
	ds_read2st64_b32 v[20:21], v7 offset0:12 offset1:13
	ds_read2st64_b32 v[22:23], v7 offset0:14 offset1:15
	s_mul_hi_u32 s0, s40, 0x2e8ba3
	s_mul_i32 s1, s0, 1408
	s_sub_u32 s1, s40, s1
	s_mul_hi_u32 s2, s1, 0x2e8ba2f
	s_mul_i32 s8, s2, 88
	s_sub_u32 s8, s1, s8
	s_lshr_b32 s9, s8, 1
	s_lshl_b32 s9, s9, 8
	s_and_b32 s28, s8, 1
	s_lshl_b32 s28, s28, 6
	s_add_u32 s9, s9, s28
	s_add_u32 s9, s9, 128
	s_mul_i32 s9, s9, 0x1000
	s_mul_i32 s28, s0, 0x2c00000
	s_add_u32 s9, s9, s28
	s_lshl_b32 s2, s2, 8
	s_add_u32 s9, s9, s2
	s_add_u32 s9, s9, 0x8000
	s_add_u32 s44, s54, s9
	s_addc_u32 s45, s55, 0
	s_waitcnt lgkmcnt(6)
	v_cvt_pk_bf16_f32 v8, v8, v9
	v_cvt_pk_bf16_f32 v9, v10, v11
	s_waitcnt lgkmcnt(4)
	v_cvt_pk_bf16_f32 v10, v12, v13
	v_cvt_pk_bf16_f32 v11, v14, v15
	s_waitcnt lgkmcnt(2)
	v_cvt_pk_bf16_f32 v12, v16, v17
	v_cvt_pk_bf16_f32 v13, v18, v19
	s_waitcnt lgkmcnt(0)
	v_cvt_pk_bf16_f32 v14, v20, v21
	v_cvt_pk_bf16_f32 v15, v22, v23
	global_store_dwordx4 v5, v[8:11], s[44:45]
	global_store_dwordx4 v5, v[12:15], s[44:45] offset:16
	s_add_u32 s40, s40, 256
	s_add_u32 s41, s41, 0x8000
	s_and_b32 s41, s41, 0x1ffff
	s_cmp_lt_u32 s40, 5632
	s_cbranch_scc1 .Lcv_up_loop
.Lcv_up_skip:
	s_mov_b32 s40, s60
	s_cmp_lt_u32 s40, 5632
	s_cbranch_scc0 .Lcv_down_skip
	v_mov_b32_e32 v29, 0x2000
	v_mov_b32_e32 v28, 0x2c00
	v_mad_u32_u24 v0, v30, v29, v31
	v_mad_u32_u24 v5, v26, v28, v27
	v_add_u32_e32 v1, 0x8000, v0
	v_add_u32_e32 v2, 0x10000, v0
	v_add_u32_e32 v3, 0x18000, v0
	s_barrier
	s_mov_b32 s41, 0
	s_mov_b32 s47, s40
	s_mov_b32 s48, s46
	s_mul_hi_u32 s0, s47, 0x2e8ba3
	s_mul_i32 s1, s0, 1408
	s_sub_u32 s1, s47, s1
	s_mul_hi_u32 s2, s1, 0x8000001
	s_mul_i32 s8, s2, 32
	s_sub_u32 s8, s1, s8
	s_mul_i32 s9, s0, 0x2c00000
	s_mul_i32 s28, s2, 0x100000
	s_add_u32 s9, s9, s28
	s_lshl_b32 s8, s8, 8
	s_add_u32 s9, s9, s8
	s_add_u32 s42, s74, s9
	s_addc_u32 s43, s75, 0
	s_mov_b32 m0, s48
	s_add_u32 s49, s48, 0x400
	global_load_lds_dwordx4 v0, s[42:43]
	s_mov_b32 m0, s49
	s_add_u32 s49, s48, 0x800
	global_load_lds_dwordx4 v1, s[42:43]
	s_mov_b32 m0, s49
	s_add_u32 s49, s48, 0xc00
	global_load_lds_dwordx4 v2, s[42:43]
	s_mov_b32 m0, s49
	s_nop 0
	global_load_lds_dwordx4 v3, s[42:43]
	global_load_dword v24, v173, s[74:75]
	global_load_dword v24, v173, s[74:75]
	s_add_u32 s47, s40, 256
	s_add_u32 s48, s46, 0x8000
	s_cmp_lt_u32 s47, 5632
	s_cbranch_scc0 .Lcv_down_pd1
	s_mul_hi_u32 s0, s47, 0x2e8ba3
	s_mul_i32 s1, s0, 1408
	s_sub_u32 s1, s47, s1
	s_mul_hi_u32 s2, s1, 0x8000001
	s_mul_i32 s8, s2, 32
	s_sub_u32 s8, s1, s8
	s_mul_i32 s9, s0, 0x2c00000
	s_mul_i32 s28, s2, 0x100000
	s_add_u32 s9, s9, s28
	s_lshl_b32 s8, s8, 8
	s_add_u32 s9, s9, s8
	s_add_u32 s42, s74, s9
	s_addc_u32 s43, s75, 0
	s_mov_b32 m0, s48
	s_add_u32 s49, s48, 0x400
	global_load_lds_dwordx4 v0, s[42:43]
	s_mov_b32 m0, s49
	s_add_u32 s49, s48, 0x800
	global_load_lds_dwordx4 v1, s[42:43]
	s_mov_b32 m0, s49
	s_add_u32 s49, s48, 0xc00
	global_load_lds_dwordx4 v2, s[42:43]
	s_mov_b32 m0, s49
	s_nop 0
	global_load_lds_dwordx4 v3, s[42:43]
	s_branch .Lcv_down_pj1
.Lcv_down_pd1:
	global_load_dword v24, v173, s[74:75]
	global_load_dword v24, v173, s[74:75]
	global_load_dword v24, v173, s[74:75]
	global_load_dword v24, v173, s[74:75]
.Lcv_down_pj1:
	global_load_dword v24, v173, s[74:75]
	global_load_dword v24, v173, s[74:75]
	s_add_u32 s47, s40, 512
	s_add_u32 s48, s46, 0x10000
	s_cmp_lt_u32 s47, 5632
	s_cbranch_scc0 .Lcv_down_pd2
	s_mul_hi_u32 s0, s47, 0x2e8ba3
	s_mul_i32 s1, s0, 1408
	s_sub_u32 s1, s47, s1
	s_mul_hi_u32 s2, s1, 0x8000001
	s_mul_i32 s8, s2, 32
	s_sub_u32 s8, s1, s8
	s_mul_i32 s9, s0, 0x2c00000
	s_mul_i32 s28, s2, 0x100000
	s_add_u32 s9, s9, s28
	s_lshl_b32 s8, s8, 8
	s_add_u32 s9, s9, s8
	s_add_u32 s42, s74, s9
	s_addc_u32 s43, s75, 0
	s_mov_b32 m0, s48
	s_add_u32 s49, s48, 0x400
	global_load_lds_dwordx4 v0, s[42:43]
	s_mov_b32 m0, s49
	s_add_u32 s49, s48, 0x800
	global_load_lds_dwordx4 v1, s[42:43]
	s_mov_b32 m0, s49
	s_add_u32 s49, s48, 0xc00
	global_load_lds_dwordx4 v2, s[42:43]
	s_mov_b32 m0, s49
	s_nop 0
	global_load_lds_dwordx4 v3, s[42:43]
	s_branch .Lcv_down_pj2

; __device__ __forceinline__ void lds_barrier() { asm volatile("s_waitcnt lgkmcnt(0)" ::: "memory"); __builtin_amdgcn_s_barrier(); asm volatile("" ::: "memory"); }
; #define CVT_LOAD(tile_) do { const int k0_ = ((tile_) / ntn) << 7, n0_ = ((tile_) % ntn) << 6; \
;         _Pragma("unroll") for (int pp = 0; pp < 4; ++pp) pv[pp] = *(const float4*)(src + (size_t)(k0_ + lk + 32 * pp) * N + n0_ + ln4); } while (0)
; __device__ __forceinline__ void convT_job(const float* __restrict__ src, bf16_t* __restrict__ dst, int K, int N, int mode, float* t) {
;     ...
; #pragma unroll 1
;     for (; tile < ntiles; tile += gridDim.x) {
;         const int k0 = (tile / ntn) << 7, n0 = (tile % ntn) << 6;
; #pragma unroll
;         for (int pp = 0; pp < 4; ++pp) { const int k = lk + 32 * pp; t[k * 65 + ln4] = pv[pp].x; t[k * 65 + ln4 + 1] = pv[pp].y; t[k * 65 + ln4 + 2] = pv[pp].z; t[k * 65 + ln4 + 3] = pv[pp].w; }
;         if (tile + (int)gridDim.x < ntiles) CVT_LOAD(tile + (int)gridDim.x);
;         lds_barrier();
.Lcv_down_pj2:
	global_load_dword v24, v173, s[74:75]
	global_load_dword v24, v173, s[74:75]
.Lcv_down_loop:
	s_waitcnt vmcnt(14)
	s_barrier
	s_add_u32 s47, s40, 768
	s_add_u32 s48, s41, 0x18000
	s_and_b32 s48, s48, 0x1ffff
	s_add_u32 s48, s48, s46
	s_cmp_lt_u32 s47, 5632
	s_cbranch_scc0 .Lcv_down_ld
	s_mul_hi_u32 s0, s47, 0x2e8ba3
	s_mul_i32 s1, s0, 1408
	s_sub_u32 s1, s47, s1
	s_mul_hi_u32 s2, s1, 0x8000001
	s_mul_i32 s8, s2, 32
	s_sub_u32 s8, s1, s8
	s_mul_i32 s9, s0, 0x2c00000
	s_mul_i32 s28, s2, 0x100000
	s_add_u32 s9, s9, s28
	s_lshl_b32 s8, s8, 8
	s_add_u32 s9, s9, s8
	s_add_u32 s42, s74, s9
	s_addc_u32 s43, s75, 0
	s_mov_b32 m0, s48
	s_add_u32 s49, s48, 0x400
	global_load_lds_dwordx4 v0, s[42:43]
	s_mov_b32 m0, s49
	s_add_u32 s49, s48, 0x800
	global_load_lds_dwordx4 v1, s[42:43]
	s_mov_b32 m0, s49
	s_add_u32 s49, s48, 0xc00
	global_load_lds_dwordx4 v2, s[42:43]
	s_mov_b32 m0, s49
	s_nop 0
	global_load_lds_dwordx4 v3, s[42:43]
	s_branch .Lcv_down_lj

; __device__ __forceinline__ unsigned cvt_pk_bf16(float lo, float hi) { unsigned r; asm volatile("v_cvt_pk_bf16_f32 %0, %1, %2" : "=v"(r) : "v"(lo), "v"(hi)); return r; }
; __device__ __forceinline__ void lds_barrier() { asm volatile("s_waitcnt lgkmcnt(0)" ::: "memory"); __builtin_amdgcn_s_barrier(); asm volatile("" ::: "memory"); }
; __device__ __forceinline__ void convT_job(const float* __restrict__ src, bf16_t* __restrict__ dst, int K, int N, int mode, float* t) {
;     ...
;         const int n = tid >> 3, k16 = (tid & 7) * 16;
;         float v[16];
; #pragma unroll
;         for (int j = 0; j < 16; ++j) v[j] = t[(k16 + j) * 65 + n];
;         const int nn = n0 + n;
;         const int row = mode == 0 ? nn : (256 * (nn >> 7) + (nn & 127) + (mode == 2 ? 128 : 0));
;         u32x4 w0, w1; w0.x = cvt_pk_bf16(v[0], v[1]); w0.y = cvt_pk_bf16(v[2], v[3]); w0.z = cvt_pk_bf16(v[4], v[5]); w0.w = cvt_pk_bf16(v[6], v[7]);
;         w1.x = cvt_pk_bf16(v[8], v[9]); w1.y = cvt_pk_bf16(v[10], v[11]); w1.z = cvt_pk_bf16(v[12], v[13]); w1.w = cvt_pk_bf16(v[14], v[15]);
;         bf16_t* d = dst + (size_t)row * K + k0 + k16;
;         *(u32x4*)d = w0; *(u32x4*)(d + 8) = w1;
;         lds_barrier();
; __device__ __forceinline__ void phase_convert(const Params& p, unsigned char* smem) {
;     ...
;         convT_job(p.in[6] + (size_t)l * 2048 * 5632, (bf16_t*)(p.ws + OFF_IN + (size_t)l * SZ_IN), 2048, 5632, 0, t);
.Lcv_down_lj:
	v_add_u32_e32 v7, s41, v4
	ds_read2st64_b32 v[8:9], v7 offset0:0 offset1:1
	ds_read2st64_b32 v[10:11], v7 offset0:2 offset1:3
	ds_read2st64_b32 v[12:13], v7 offset0:4 offset1:5
	ds_read2st64_b32 v[14:15], v7 offset0:6 offset1:7
	ds_read2st64_b32 v[16:17], v7 offset0:8 offset1:9
	ds_read2st64_b32 v[18:19], v7 offset0:10 offset1:11
	ds_read2st64_b32 v[20:21], v7 offset0:12 offset1:13
	ds_read2st64_b32 v[22:23], v7 offset0:14 offset1:15
	s_mul_hi_u32 s0, s40, 0x2e8ba3
	s_mul_i32 s1, s0, 1408
	s_sub_u32 s1, s40, s1
	s_mul_hi_u32 s2, s1, 0x8000001
	s_mul_i32 s8, s2, 32
	s_sub_u32 s8, s1, s8
	s_lshl_b32 s9, s8, 6
	s_mul_i32 s9, s9, 0x2c00
	s_mul_i32 s28, s0, 0x1600000
	s_add_u32 s9, s9, s28
	s_lshl_b32 s2, s2, 8
	s_add_u32 s9, s9, s2
	s_add_u32 s9, s9, 0xb008000
	s_add_u32 s44, s54, s9
	s_addc_u32 s45, s55, 0
	s_waitcnt lgkmcnt(6)
	v_cvt_pk_bf16_f32 v8, v8, v9
	v_cvt_pk_bf16_f32 v9, v10, v11
	s_waitcnt lgkmcnt(4)
	v_cvt_pk_bf16_f32 v10, v12, v13
	v_cvt_pk_bf16_f32 v11, v14, v15
	s_waitcnt lgkmcnt(2)
	v_cvt_pk_bf16_f32 v12, v16, v17
	v_cvt_pk_bf16_f32 v13, v18, v19
	s_waitcnt lgkmcnt(0)
	v_cvt_pk_bf16_f32 v14, v20, v21
	v_cvt_pk_bf16_f32 v15, v22, v23
	global_store_dwordx4 v5, v[8:11], s[44:45]
	global_store_dwordx4 v5, v[12:15], s[44:45] offset:16
	s_add_u32 s40, s40, 256
	s_add_u32 s41, s41, 0x8000
	s_and_b32 s41, s41, 0x1ffff
	s_cmp_lt_u32 s40, 5632
	s_cbranch_scc1 .Lcv_down_loop
.Lcv_down_skip:
	s_mov_b32 s40, s60
	s_cmp_lt_u32 s40, 2816
	s_cbranch_scc0 .Lcv_win_skip
	v_mov_b32_e32 v29, 0x5800
	v_mov_b32_e32 v28, 0x1000
	v_mad_u32_u24 v0, v30, v29, v31
	v_mad_u32_u24 v5, v26, v28, v27
	v_add_u32_e32 v1, 0x16000, v0
	v_add_u32_e32 v2, 0x2c000, v0
	v_add_u32_e32 v3, 0x42000, v0
	s_barrier
	s_mov_b32 s41, 0
	s_mov_b32 s47, s40
	s_mov_b32 s48, s46
	s_mul_hi_u32 s0, s47, 0x2e8ba3
	s_mul_i32 s1, s0, 1408
	s_sub_u32 s1, s47, s1
	s_mul_hi_u32 s2, s1, 0x2e8ba2f
	s_mul_i32 s8, s2, 88
	s_sub_u32 s8, s1, s8
	s_mul_i32 s9, s0, 0x2c00000
	s_mul_i32 s28, s2, 0x2c0000
	s_add_u32 s9, s9, s28
	s_lshl_b32 s8, s8, 8
	s_add_u32 s9, s9, s8
	s_add_u32 s42, s76, s9
	s_addc_u32 s43, s77, 0
	s_mov_b32 m0, s48
	s_add_u32 s49, s48, 0x400
	global_load_lds_dwordx4 v0, s[42:43]
	s_mov_b32 m0, s49
	s_add_u32 s49, s48, 0x800
	global_load_lds_dwordx4 v1, s[42:43]
	s_mov_b32 m0, s49
	s_add_u32 s49, s48, 0xc00
	global_load_lds_dwordx4 v2, s[42:43]
	s_mov_b32 m0, s49
	s_nop 0
	global_load_lds_dwordx4 v3, s[42:43]
	global_load_dword v24, v173, s[76:77]
	global_load_dword v24, v173, s[76:77]
	s_add_u32 s47, s40, 256
	s_add_u32 s48, s46, 0x8000
	s_cmp_lt_u32 s47, 2816
	s_cbranch_scc0 .Lcv_win_pd1
	s_mul_hi_u32 s0, s47, 0x2e8ba3
	s_mul_i32 s1, s0, 1408
	s_sub_u32 s1, s47, s1
	s_mul_hi_u32 s2, s1, 0x2e8ba2f
	s_mul_i32 s8, s2, 88
	s_sub_u32 s8, s1, s8
	s_mul_i32 s9, s0, 0x2c00000
	s_mul_i32 s28, s2, 0x2c0000
	s_add_u32 s9, s9, s28
	s_lshl_b32 s8, s8, 8
	s_add_u32 s9, s9, s8
	s_add_u32 s42, s76, s9
	s_addc_u32 s43, s77, 0
	s_mov_b32 m0, s48
	s_add_u32 s49, s48, 0x400
	global_load_lds_dwordx4 v0, s[42:43]
	s_mov_b32 m0, s49
	s_add_u32 s49, s48, 0x800
	global_load_lds_dwordx4 v1, s[42:43]
	s_mov_b32 m0, s49
	s_add_u32 s49, s48, 0xc00
	global_load_lds_dwordx4 v2, s[42:43]
	s_mov_b32 m0, s49
	s_nop 0
	global_load_lds_dwordx4 v3, s[42:43]
	s_branch .Lcv_win_pj1
.Lcv_win_pd1:
	global_load_dword v24, v173, s[76:77]
	global_load_dword v24, v173, s[76:77]
	global_load_dword v24, v173, s[76:77]
	global_load_dword v24, v173, s[76:77]
.Lcv_win_pj1:
	global_load_dword v24, v173, s[76:77]
	global_load_dword v24, v173, s[76:77]
	s_add_u32 s47, s40, 512
	s_add_u32 s48, s46, 0x10000
	s_cmp_lt_u32 s47, 2816
	s_cbranch_scc0 .Lcv_win_pd2
	s_mul_hi_u32 s0, s47, 0x2e8ba3
	s_mul_i32 s1, s0, 1408
	s_sub_u32 s1, s47, s1
	s_mul_hi_u32 s2, s1, 0x2e8ba2f
	s_mul_i32 s8, s2, 88
	s_sub_u32 s8, s1, s8
	s_mul_i32 s9, s0, 0x2c00000
	s_mul_i32 s28, s2, 0x2c0000
	s_add_u32 s9, s9, s28
	s_lshl_b32 s8, s8, 8
	s_add_u32 s9, s9, s8
	s_add_u32 s42, s76, s9
	s_addc_u32 s43, s77, 0
	s_mov_b32 m0, s48
	s_add_u32 s49, s48, 0x400
	global_load_lds_dwordx4 v0, s[42:43]
	s_mov_b32 m0, s49
	s_add_u32 s49, s48, 0x800
	global_load_lds_dwordx4 v1, s[42:43]
	s_mov_b32 m0, s49
	s_add_u32 s49, s48, 0xc00
	global_load_lds_dwordx4 v2, s[42:43]
	s_mov_b32 m0, s49
	s_nop 0
	global_load_lds_dwordx4 v3, s[42:43]
	s_branch .Lcv_win_pj2

; __device__ __forceinline__ void lds_barrier() { asm volatile("s_waitcnt lgkmcnt(0)" ::: "memory"); __builtin_amdgcn_s_barrier(); asm volatile("" ::: "memory"); }
; #define CVT_LOAD(tile_) do { const int k0_ = ((tile_) / ntn) << 7, n0_ = ((tile_) % ntn) << 6; \
;         _Pragma("unroll") for (int pp = 0; pp < 4; ++pp) pv[pp] = *(const float4*)(src + (size_t)(k0_ + lk + 32 * pp) * N + n0_ + ln4); } while (0)
; __device__ __forceinline__ void convT_job(const float* __restrict__ src, bf16_t* __restrict__ dst, int K, int N, int mode, float* t) {
;     ...
; #pragma unroll 1
;     for (; tile < ntiles; tile += gridDim.x) {
;         const int k0 = (tile / ntn) << 7, n0 = (tile % ntn) << 6;
; #pragma unroll
;         for (int pp = 0; pp < 4; ++pp) { const int k = lk + 32 * pp; t[k * 65 + ln4] = pv[pp].x; t[k * 65 + ln4 + 1] = pv[pp].y; t[k * 65 + ln4 + 2] = pv[pp].z; t[k * 65 + ln4 + 3] = pv[pp].w; }
;         if (tile + (int)gridDim.x < ntiles) CVT_LOAD(tile + (int)gridDim.x);
;         lds_barrier();
.Lcv_win_pj2:
	global_load_dword v24, v173, s[76:77]
	global_load_dword v24, v173, s[76:77]
.Lcv_win_loop:
	s_waitcnt vmcnt(14)
	s_barrier
	s_add_u32 s47, s40, 768
	s_add_u32 s48, s41, 0x18000
	s_and_b32 s48, s48, 0x1ffff
	s_add_u32 s48, s48, s46
	s_cmp_lt_u32 s47, 2816
	s_cbranch_scc0 .Lcv_win_ld
	s_mul_hi_u32 s0, s47, 0x2e8ba3
	s_mul_i32 s1, s0, 1408
	s_sub_u32 s1, s47, s1
	s_mul_hi_u32 s2, s1, 0x2e8ba2f
	s_mul_i32 s8, s2, 88
	s_sub_u32 s8, s1, s8
	s_mul_i32 s9, s0, 0x2c00000
	s_mul_i32 s28, s2, 0x2c0000
	s_add_u32 s9, s9, s28
	s_lshl_b32 s8, s8, 8
	s_add_u32 s9, s9, s8
	s_add_u32 s42, s76, s9
	s_addc_u32 s43, s77, 0
	s_mov_b32 m0, s48
	s_add_u32 s49, s48, 0x400
	global_load_lds_dwordx4 v0, s[42:43]
	s_mov_b32 m0, s49
	s_add_u32 s49, s48, 0x800
	global_load_lds_dwordx4 v1, s[42:43]
	s_mov_b32 m0, s49
	s_add_u32 s49, s48, 0xc00
	global_load_lds_dwordx4 v2, s[42:43]
	s_mov_b32 m0, s49
	s_nop 0
	global_load_lds_dwordx4 v3, s[42:43]
	s_branch .Lcv_win_lj

; __device__ __forceinline__ unsigned cvt_pk_bf16(float lo, float hi) { unsigned r; asm volatile("v_cvt_pk_bf16_f32 %0, %1, %2" : "=v"(r) : "v"(lo), "v"(hi)); return r; }
; __device__ __forceinline__ void lds_barrier() { asm volatile("s_waitcnt lgkmcnt(0)" ::: "memory"); __builtin_amdgcn_s_barrier(); asm volatile("" ::: "memory"); }
; __device__ __forceinline__ void convT_job(const float* __restrict__ src, bf16_t* __restrict__ dst, int K, int N, int mode, float* t) {
;     ...
;         const int n = tid >> 3, k16 = (tid & 7) * 16;
;         float v[16];
; #pragma unroll
;         for (int j = 0; j < 16; ++j) v[j] = t[(k16 + j) * 65 + n];
;         const int nn = n0 + n;
;         const int row = mode == 0 ? nn : (256 * (nn >> 7) + (nn & 127) + (mode == 2 ? 128 : 0));
;         u32x4 w0, w1; w0.x = cvt_pk_bf16(v[0], v[1]); w0.y = cvt_pk_bf16(v[2], v[3]); w0.z = cvt_pk_bf16(v[4], v[5]); w0.w = cvt_pk_bf16(v[6], v[7]);
;         w1.x = cvt_pk_bf16(v[8], v[9]); w1.y = cvt_pk_bf16(v[10], v[11]); w1.z = cvt_pk_bf16(v[12], v[13]); w1.w = cvt_pk_bf16(v[14], v[15]);
;         bf16_t* d = dst + (size_t)row * K + k0 + k16;
;         *(u32x4*)d = w0; *(u32x4*)(d + 8) = w1;
;         lds_barrier();
; __device__ __forceinline__ void phase_convert(const Params& p, unsigned char* smem) {
;     ...
;         convT_job(p.in[7] + (size_t)l * 2048 * 2048, (bf16_t*)(p.ws + OFF_OUT + (size_t)l * SZ_OUT), 2048, 2048, 0, t);
.Lcv_win_lj:
	v_add_u32_e32 v7, s41, v4
	ds_read2st64_b32 v[8:9], v7 offset0:0 offset1:1
	ds_read2st64_b32 v[10:11], v7 offset0:2 offset1:3
	ds_read2st64_b32 v[12:13], v7 offset0:4 offset1:5
	ds_read2st64_b32 v[14:15], v7 offset0:6 offset1:7
	ds_read2st64_b32 v[16:17], v7 offset0:8 offset1:9
	ds_read2st64_b32 v[18:19], v7 offset0:10 offset1:11
	ds_read2st64_b32 v[20:21], v7 offset0:12 offset1:13
	ds_read2st64_b32 v[22:23], v7 offset0:14 offset1:15
	s_mul_hi_u32 s0, s40, 0x2e8ba3
	s_mul_i32 s1, s0, 1408
	s_sub_u32 s1, s40, s1
	s_mul_hi_u32 s2, s1, 0x2e8ba2f
	s_mul_i32 s8, s2, 88
	s_sub_u32 s8, s1, s8
	s_lshl_b32 s9, s8, 6
	s_mul_i32 s9, s9, 0x1000
	s_mul_i32 s28, s0, 0x1600000
	s_add_u32 s9, s9, s28
	s_lshl_b32 s2, s2, 8
	s_add_u32 s9, s9, s2
	s_add_u32 s9, s9, 0x10808000
	s_add_u32 s44, s54, s9
	s_addc_u32 s45, s55, 0
	s_waitcnt lgkmcnt(6)
	v_cvt_pk_bf16_f32 v8, v8, v9
	v_cvt_pk_bf16_f32 v9, v10, v11
	s_waitcnt lgkmcnt(4)
	v_cvt_pk_bf16_f32 v10, v12, v13
	v_cvt_pk_bf16_f32 v11, v14, v15
	s_waitcnt lgkmcnt(2)
	v_cvt_pk_bf16_f32 v12, v16, v17
	v_cvt_pk_bf16_f32 v13, v18, v19
	s_waitcnt lgkmcnt(0)
	v_cvt_pk_bf16_f32 v14, v20, v21
	v_cvt_pk_bf16_f32 v15, v22, v23
	global_store_dwordx4 v5, v[8:11], s[44:45]
	global_store_dwordx4 v5, v[12:15], s[44:45] offset:16
	s_add_u32 s40, s40, 256
	s_add_u32 s41, s41, 0x8000
	s_and_b32 s41, s41, 0x1ffff
	s_cmp_lt_u32 s40, 2816
	s_cbranch_scc1 .Lcv_win_loop
.Lcv_win_skip:
	s_mov_b32 s40, s60
	s_cmp_lt_u32 s40, 1024
	s_cbranch_scc0 .Lcv_wout_skip
	v_mov_b32_e32 v29, 0x2000
	v_mov_b32_e32 v28, 0x1000
	v_mad_u32_u24 v0, v30, v29, v31
	v_mad_u32_u24 v5, v26, v28, v27
	v_add_u32_e32 v1, 0x8000, v0
	v_add_u32_e32 v2, 0x10000, v0
	v_add_u32_e32 v3, 0x18000, v0
	s_barrier
	s_mov_b32 s41, 0
	s_mov_b32 s47, s40
	s_mov_b32 s48, s46
	s_mul_hi_u32 s0, s47, 0x800001
	s_mul_i32 s1, s0, 512
	s_sub_u32 s1, s47, s1
	s_mul_hi_u32 s2, s1, 0x8000001
	s_mul_i32 s8, s2, 32
	s_sub_u32 s8, s1, s8
	s_mul_i32 s9, s0, 0x1000000
	s_mul_i32 s28, s2, 0x100000
	s_add_u32 s9, s9, s28
	s_lshl_b32 s8, s8, 8
	s_add_u32 s9, s9, s8
	s_add_u32 s42, s78, s9
	s_addc_u32 s43, s79, 0
	s_mov_b32 m0, s48
	s_add_u32 s49, s48, 0x400
	global_load_lds_dwordx4 v0, s[42:43]
	s_mov_b32 m0, s49
	s_add_u32 s49, s48, 0x800
	global_load_lds_dwordx4 v1, s[42:43]
	s_mov_b32 m0, s49
	s_add_u32 s49, s48, 0xc00
	global_load_lds_dwordx4 v2, s[42:43]
	s_mov_b32 m0, s49
	s_nop 0
	global_load_lds_dwordx4 v3, s[42:43]
	global_load_dword v24, v173, s[78:79]
	global_load_dword v24, v173, s[78:79]
	s_add_u32 s47, s40, 256
	s_add_u32 s48, s46, 0x8000
	s_cmp_lt_u32 s47, 1024
	s_cbranch_scc0 .Lcv_wout_pd1
	s_mul_hi_u32 s0, s47, 0x800001
	s_mul_i32 s1, s0, 512
	s_sub_u32 s1, s47, s1
	s_mul_hi_u32 s2, s1, 0x8000001
	s_mul_i32 s8, s2, 32
	s_sub_u32 s8, s1, s8
	s_mul_i32 s9, s0, 0x1000000
	s_mul_i32 s28, s2, 0x100000
	s_add_u32 s9, s9, s28
	s_lshl_b32 s8, s8, 8
	s_add_u32 s9, s9, s8
	s_add_u32 s42, s78, s9
	s_addc_u32 s43, s79, 0
	s_mov_b32 m0, s48
	s_add_u32 s49, s48, 0x400
	global_load_lds_dwordx4 v0, s[42:43]
	s_mov_b32 m0, s49
	s_add_u32 s49, s48, 0x800
	global_load_lds_dwordx4 v1, s[42:43]
	s_mov_b32 m0, s49
	s_add_u32 s49, s48, 0xc00
	global_load_lds_dwordx4 v2, s[42:43]
	s_mov_b32 m0, s49
	s_nop 0
	global_load_lds_dwordx4 v3, s[42:43]
	s_branch .Lcv_wout_pj1
.Lcv_wout_pd1:
	global_load_dword v24, v173, s[78:79]
	global_load_dword v24, v173, s[78:79]
	global_load_dword v24, v173, s[78:79]
	global_load_dword v24, v173, s[78:79]
.Lcv_wout_pj1:
	global_load_dword v24, v173, s[78:79]
	global_load_dword v24, v173, s[78:79]
	s_add_u32 s47, s40, 512
	s_add_u32 s48, s46, 0x10000
	s_cmp_lt_u32 s47, 1024
	s_cbranch_scc0 .Lcv_wout_pd2
	s_mul_hi_u32 s0, s47, 0x800001
	s_mul_i32 s1, s0, 512
	s_sub_u32 s1, s47, s1
	s_mul_hi_u32 s2, s1, 0x8000001
	s_mul_i32 s8, s2, 32
	s_sub_u32 s8, s1, s8
	s_mul_i32 s9, s0, 0x1000000
	s_mul_i32 s28, s2, 0x100000
	s_add_u32 s9, s9, s28
	s_lshl_b32 s8, s8, 8
	s_add_u32 s9, s9, s8
	s_add_u32 s42, s78, s9
	s_addc_u32 s43, s79, 0
	s_mov_b32 m0, s48
	s_add_u32 s49, s48, 0x400
	global_load_lds_dwordx4 v0, s[42:43]
	s_mov_b32 m0, s49
	s_add_u32 s49, s48, 0x800
	global_load_lds_dwordx4 v1, s[42:43]
	s_mov_b32 m0, s49
	s_add_u32 s49, s48, 0xc00
	global_load_lds_dwordx4 v2, s[42:43]
	s_mov_b32 m0, s49
	s_nop 0
	global_load_lds_dwordx4 v3, s[42:43]
	s_branch .Lcv_wout_pj2

; __device__ __forceinline__ void lds_barrier() { asm volatile("s_waitcnt lgkmcnt(0)" ::: "memory"); __builtin_amdgcn_s_barrier(); asm volatile("" ::: "memory"); }
; #define CVT_LOAD(tile_) do { const int k0_ = ((tile_) / ntn) << 7, n0_ = ((tile_) % ntn) << 6; \
;         _Pragma("unroll") for (int pp = 0; pp < 4; ++pp) pv[pp] = *(const float4*)(src + (size_t)(k0_ + lk + 32 * pp) * N + n0_ + ln4); } while (0)
; __device__ __forceinline__ void convT_job(const float* __restrict__ src, bf16_t* __restrict__ dst, int K, int N, int mode, float* t) {
;     ...
; #pragma unroll 1
;     for (; tile < ntiles; tile += gridDim.x) {
;         const int k0 = (tile / ntn) << 7, n0 = (tile % ntn) << 6;
; #pragma unroll
;         for (int pp = 0; pp < 4; ++pp) { const int k = lk + 32 * pp; t[k * 65 + ln4] = pv[pp].x; t[k * 65 + ln4 + 1] = pv[pp].y; t[k * 65 + ln4 + 2] = pv[pp].z; t[k * 65 + ln4 + 3] = pv[pp].w; }
;         if (tile + (int)gridDim.x < ntiles) CVT_LOAD(tile + (int)gridDim.x);
;         lds_barrier();
.Lcv_wout_pj2:
	global_load_dword v24, v173, s[78:79]
	global_load_dword v24, v173, s[78:79]
.Lcv_wout_loop:
	s_waitcnt vmcnt(14)
	s_barrier
	s_add_u32 s47, s40, 768
	s_add_u32 s48, s41, 0x18000
	s_and_b32 s48, s48, 0x1ffff
	s_add_u32 s48, s48, s46
	s_cmp_lt_u32 s47, 1024
	s_cbranch_scc0 .Lcv_wout_ld
	s_mul_hi_u32 s0, s47, 0x800001
	s_mul_i32 s1, s0, 512
	s_sub_u32 s1, s47, s1
	s_mul_hi_u32 s2, s1, 0x8000001
	s_mul_i32 s8, s2, 32
	s_sub_u32 s8, s1, s8
	s_mul_i32 s9, s0, 0x1000000
	s_mul_i32 s28, s2, 0x100000
	s_add_u32 s9, s9, s28
	s_lshl_b32 s8, s8, 8
	s_add_u32 s9, s9, s8
	s_add_u32 s42, s78, s9
	s_addc_u32 s43, s79, 0
	s_mov_b32 m0, s48
	s_add_u32 s49, s48, 0x400
	global_load_lds_dwordx4 v0, s[42:43]
	s_mov_b32 m0, s49
	s_add_u32 s49, s48, 0x800
	global_load_lds_dwordx4 v1, s[42:43]
	s_mov_b32 m0, s49
	s_add_u32 s49, s48, 0xc00
	global_load_lds_dwordx4 v2, s[42:43]
	s_mov_b32 m0, s49
	s_nop 0
	global_load_lds_dwordx4 v3, s[42:43]
	s_branch .Lcv_wout_lj

; __device__ __forceinline__ unsigned cvt_pk_bf16(float lo, float hi) { unsigned r; asm volatile("v_cvt_pk_bf16_f32 %0, %1, %2" : "=v"(r) : "v"(lo), "v"(hi)); return r; }
; __device__ __forceinline__ void lds_barrier() { asm volatile("s_waitcnt lgkmcnt(0)" ::: "memory"); __builtin_amdgcn_s_barrier(); asm volatile("" ::: "memory"); }
; __device__ __forceinline__ void convT_job(const float* __restrict__ src, bf16_t* __restrict__ dst, int K, int N, int mode, float* t) {
;     ...
;         const int n = tid >> 3, k16 = (tid & 7) * 16;
;         float v[16];
; #pragma unroll
;         for (int j = 0; j < 16; ++j) v[j] = t[(k16 + j) * 65 + n];
;         const int nn = n0 + n;
;         const int row = mode == 0 ? nn : (256 * (nn >> 7) + (nn & 127) + (mode == 2 ? 128 : 0));
;         u32x4 w0, w1; w0.x = cvt_pk_bf16(v[0], v[1]); w0.y = cvt_pk_bf16(v[2], v[3]); w0.z = cvt_pk_bf16(v[4], v[5]); w0.w = cvt_pk_bf16(v[6], v[7]);
;         w1.x = cvt_pk_bf16(v[8], v[9]); w1.y = cvt_pk_bf16(v[10], v[11]); w1.z = cvt_pk_bf16(v[12], v[13]); w1.w = cvt_pk_bf16(v[14], v[15]);
;         bf16_t* d = dst + (size_t)row * K + k0 + k16;
;         *(u32x4*)d = w0; *(u32x4*)(d + 8) = w1;
;         lds_barrier();
; __device__ __forceinline__ void phase_convert(const Params& p, unsigned char* smem) {
;     ...
;             convT_job(p.in[10] + (size_t)(l * 4 + g) * 16384, (bf16_t*)(p.ws + OFF_RGA + (size_t)l * SZ_RG) + g * 16384, 128, 128, 0, t);
.Lcv_wout_lj:
	v_add_u32_e32 v7, s41, v4
	ds_read2st64_b32 v[8:9], v7 offset0:0 offset1:1
	ds_read2st64_b32 v[10:11], v7 offset0:2 offset1:3
	ds_read2st64_b32 v[12:13], v7 offset0:4 offset1:5
	ds_read2st64_b32 v[14:15], v7 offset0:6 offset1:7
	ds_read2st64_b32 v[16:17], v7 offset0:8 offset1:9
	ds_read2st64_b32 v[18:19], v7 offset0:10 offset1:11
	ds_read2st64_b32 v[20:21], v7 offset0:12 offset1:13
	ds_read2st64_b32 v[22:23], v7 offset0:14 offset1:15
	s_mul_hi_u32 s0, s40, 0x800001
	s_mul_i32 s1, s0, 512
	s_sub_u32 s1, s40, s1
	s_mul_hi_u32 s2, s1, 0x8000001
	s_mul_i32 s8, s2, 32
	s_sub_u32 s8, s1, s8
	s_lshl_b32 s9, s8, 6
	s_mul_i32 s9, s9, 0x1000
	s_mul_i32 s28, s0, 0x800000
	s_add_u32 s9, s9, s28
	s_lshl_b32 s2, s2, 8
	s_add_u32 s9, s9, s2
	s_add_u32 s9, s9, 0x13408000
	s_add_u32 s44, s54, s9
	s_addc_u32 s45, s55, 0
	s_waitcnt lgkmcnt(6)
	v_cvt_pk_bf16_f32 v8, v8, v9
	v_cvt_pk_bf16_f32 v9, v10, v11
	s_waitcnt lgkmcnt(4)
	v_cvt_pk_bf16_f32 v10, v12, v13
	v_cvt_pk_bf16_f32 v11, v14, v15
	s_waitcnt lgkmcnt(2)
	v_cvt_pk_bf16_f32 v12, v16, v17
	v_cvt_pk_bf16_f32 v13, v18, v19
	s_waitcnt lgkmcnt(0)
	v_cvt_pk_bf16_f32 v14, v20, v21
	v_cvt_pk_bf16_f32 v15, v22, v23
	global_store_dwordx4 v5, v[8:11], s[44:45]
	global_store_dwordx4 v5, v[12:15], s[44:45] offset:16
	s_add_u32 s40, s40, 256
	s_add_u32 s41, s41, 0x8000
	s_and_b32 s41, s41, 0x1ffff
	s_cmp_lt_u32 s40, 1024
	s_cbranch_scc1 .Lcv_wout_loop
.Lcv_wout_skip:
	s_mov_b32 s40, s60
	s_cmp_lt_u32 s40, 16
	s_cbranch_scc0 .Lcv_rga_skip
	v_mov_b32_e32 v29, 0x200
	v_mov_b32_e32 v28, 0x100
	v_mad_u32_u24 v0, v30, v29, v31
	v_mad_u32_u24 v5, v26, v28, v27
	v_add_u32_e32 v1, 0x800, v0
	v_add_u32_e32 v2, 0x1000, v0
	v_add_u32_e32 v3, 0x1800, v0
	s_barrier
	s_mov_b32 s41, 0
	s_mov_b32 s47, s40
	s_mov_b32 s48, s46
	s_mul_hi_u32 s0, s47, 0x80000001
	s_mul_i32 s1, s0, 2
	s_sub_u32 s1, s47, s1
	s_mul_hi_u32 s2, s1, 0x80000001
	s_mul_i32 s8, s2, 2
	s_sub_u32 s8, s1, s8
	s_mul_i32 s9, s0, 0x10000
	s_mul_i32 s28, s2, 0x10000
	s_add_u32 s9, s9, s28
	s_lshl_b32 s8, s8, 8
	s_add_u32 s9, s9, s8
	s_add_u32 s42, s84, s9
	s_addc_u32 s43, s85, 0
	s_mov_b32 m0, s48
	s_add_u32 s49, s48, 0x400
	global_load_lds_dwordx4 v0, s[42:43]
	s_mov_b32 m0, s49
	s_add_u32 s49, s48, 0x800
	global_load_lds_dwordx4 v1, s[42:43]
	s_mov_b32 m0, s49
	s_add_u32 s49, s48, 0xc00
	global_load_lds_dwordx4 v2, s[42:43]
	s_mov_b32 m0, s49
	s_nop 0
	global_load_lds_dwordx4 v3, s[42:43]
	global_load_dword v24, v173, s[84:85]
	global_load_dword v24, v173, s[84:85]
	s_add_u32 s47, s40, 256
	s_add_u32 s48, s46, 0x8000
	s_cmp_lt_u32 s47, 16
	s_cbranch_scc0 .Lcv_rga_pd1
	s_mul_hi_u32 s0, s47, 0x80000001
	s_mul_i32 s1, s0, 2
	s_sub_u32 s1, s47, s1
	s_mul_hi_u32 s2, s1, 0x80000001
	s_mul_i32 s8, s2, 2
	s_sub_u32 s8, s1, s8
	s_mul_i32 s9, s0, 0x10000
	s_mul_i32 s28, s2, 0x10000
	s_add_u32 s9, s9, s28
	s_lshl_b32 s8, s8, 8
	s_add_u32 s9, s9, s8
	s_add_u32 s42, s84, s9
	s_addc_u32 s43, s85, 0
	s_mov_b32 m0, s48
	s_add_u32 s49, s48, 0x400
	global_load_lds_dwordx4 v0, s[42:43]
	s_mov_b32 m0, s49
	s_add_u32 s49, s48, 0x800
	global_load_lds_dwordx4 v1, s[42:43]
	s_mov_b32 m0, s49
	s_add_u32 s49, s48, 0xc00
	global_load_lds_dwordx4 v2, s[42:43]
	s_mov_b32 m0, s49
	s_nop 0
	global_load_lds_dwordx4 v3, s[42:43]
	s_branch .Lcv_rga_pj1
.Lcv_rga_pd1:
	global_load_dword v24, v173, s[84:85]
	global_load_dword v24, v173, s[84:85]
	global_load_dword v24, v173, s[84:85]
	global_load_dword v24, v173, s[84:85]
.Lcv_rga_pj1:
	global_load_dword v24, v173, s[84:85]
	global_load_dword v24, v173, s[84:85]
	s_add_u32 s47, s40, 512
	s_add_u32 s48, s46, 0x10000
	s_cmp_lt_u32 s47, 16
	s_cbranch_scc0 .Lcv_rga_pd2
	s_mul_hi_u32 s0, s47, 0x80000001
	s_mul_i32 s1, s0, 2
	s_sub_u32 s1, s47, s1
	s_mul_hi_u32 s2, s1, 0x80000001
	s_mul_i32 s8, s2, 2
	s_sub_u32 s8, s1, s8
	s_mul_i32 s9, s0, 0x10000
	s_mul_i32 s28, s2, 0x10000
	s_add_u32 s9, s9, s28
	s_lshl_b32 s8, s8, 8
	s_add_u32 s9, s9, s8
	s_add_u32 s42, s84, s9
	s_addc_u32 s43, s85, 0
	s_mov_b32 m0, s48
	s_add_u32 s49, s48, 0x400
	global_load_lds_dwordx4 v0, s[42:43]
	s_mov_b32 m0, s49
	s_add_u32 s49, s48, 0x800
	global_load_lds_dwordx4 v1, s[42:43]
	s_mov_b32 m0, s49
	s_add_u32 s49, s48, 0xc00
	global_load_lds_dwordx4 v2, s[42:43]
	s_mov_b32 m0, s49
	s_nop 0
	global_load_lds_dwordx4 v3, s[42:43]
	s_branch .Lcv_rga_pj2

; __device__ __forceinline__ void lds_barrier() { asm volatile("s_waitcnt lgkmcnt(0)" ::: "memory"); __builtin_amdgcn_s_barrier(); asm volatile("" ::: "memory"); }
; #define CVT_LOAD(tile_) do { const int k0_ = ((tile_) / ntn) << 7, n0_ = ((tile_) % ntn) << 6; \
;         _Pragma("unroll") for (int pp = 0; pp < 4; ++pp) pv[pp] = *(const float4*)(src + (size_t)(k0_ + lk + 32 * pp) * N + n0_ + ln4); } while (0)
; __device__ __forceinline__ void convT_job(const float* __restrict__ src, bf16_t* __restrict__ dst, int K, int N, int mode, float* t) {
;     ...
; #pragma unroll 1
;     for (; tile < ntiles; tile += gridDim.x) {
;         const int k0 = (tile / ntn) << 7, n0 = (tile % ntn) << 6;
; #pragma unroll
;         for (int pp = 0; pp < 4; ++pp) { const int k = lk + 32 * pp; t[k * 65 + ln4] = pv[pp].x; t[k * 65 + ln4 + 1] = pv[pp].y; t[k * 65 + ln4 + 2] = pv[pp].z; t[k * 65 + ln4 + 3] = pv[pp].w; }
;         if (tile + (int)gridDim.x < ntiles) CVT_LOAD(tile + (int)gridDim.x);
;         lds_barrier();
.Lcv_rga_pj2:
	global_load_dword v24, v173, s[84:85]
	global_load_dword v24, v173, s[84:85]
.Lcv_rga_loop:
	s_waitcnt vmcnt(14)
	s_barrier
	s_add_u32 s47, s40, 768
	s_add_u32 s48, s41, 0x18000
	s_and_b32 s48, s48, 0x1ffff
	s_add_u32 s48, s48, s46
	s_cmp_lt_u32 s47, 16
	s_cbranch_scc0 .Lcv_rga_ld
	s_mul_hi_u32 s0, s47, 0x80000001
	s_mul_i32 s1, s0, 2
	s_sub_u32 s1, s47, s1
	s_mul_hi_u32 s2, s1, 0x80000001
	s_mul_i32 s8, s2, 2
	s_sub_u32 s8, s1, s8
	s_mul_i32 s9, s0, 0x10000
	s_mul_i32 s28, s2, 0x10000
	s_add_u32 s9, s9, s28
	s_lshl_b32 s8, s8, 8
	s_add_u32 s9, s9, s8
	s_add_u32 s42, s84, s9
	s_addc_u32 s43, s85, 0
	s_mov_b32 m0, s48
	s_add_u32 s49, s48, 0x400
	global_load_lds_dwordx4 v0, s[42:43]
	s_mov_b32 m0, s49
	s_add_u32 s49, s48, 0x800
	global_load_lds_dwordx4 v1, s[42:43]
	s_mov_b32 m0, s49
	s_add_u32 s49, s48, 0xc00
	global_load_lds_dwordx4 v2, s[42:43]
	s_mov_b32 m0, s49
	s_nop 0
	global_load_lds_dwordx4 v3, s[42:43]
	s_branch .Lcv_rga_lj

; __device__ __forceinline__ unsigned cvt_pk_bf16(float lo, float hi) { unsigned r; asm volatile("v_cvt_pk_bf16_f32 %0, %1, %2" : "=v"(r) : "v"(lo), "v"(hi)); return r; }
; __device__ __forceinline__ void lds_barrier() { asm volatile("s_waitcnt lgkmcnt(0)" ::: "memory"); __builtin_amdgcn_s_barrier(); asm volatile("" ::: "memory"); }
; __device__ __forceinline__ void convT_job(const float* __restrict__ src, bf16_t* __restrict__ dst, int K, int N, int mode, float* t) {
;     ...
;         const int n = tid >> 3, k16 = (tid & 7) * 16;
;         float v[16];
; #pragma unroll
;         for (int j = 0; j < 16; ++j) v[j] = t[(k16 + j) * 65 + n];
;         const int nn = n0 + n;
;         const int row = mode == 0 ? nn : (256 * (nn >> 7) + (nn & 127) + (mode == 2 ? 128 : 0));
;         u32x4 w0, w1; w0.x = cvt_pk_bf16(v[0], v[1]); w0.y = cvt_pk_bf16(v[2], v[3]); w0.z = cvt_pk_bf16(v[4], v[5]); w0.w = cvt_pk_bf16(v[6], v[7]);
;         w1.x = cvt_pk_bf16(v[8], v[9]); w1.y = cvt_pk_bf16(v[10], v[11]); w1.z = cvt_pk_bf16(v[12], v[13]); w1.w = cvt_pk_bf16(v[14], v[15]);
;         bf16_t* d = dst + (size_t)row * K + k0 + k16;
;         *(u32x4*)d = w0; *(u32x4*)(d + 8) = w1;
;         lds_barrier();
; __device__ __forceinline__ void phase_convert(const Params& p, unsigned char* smem) {
;     ...
;             convT_job(p.in[12] + (size_t)(l * 4 + g) * 16384, (bf16_t*)(p.ws + OFF_RGX + (size_t)l * SZ_RG) + g * 16384, 128, 128, 0, t);
.Lcv_rga_lj:
	v_add_u32_e32 v7, s41, v4
	ds_read2st64_b32 v[8:9], v7 offset0:0 offset1:1
	ds_read2st64_b32 v[10:11], v7 offset0:2 offset1:3
	ds_read2st64_b32 v[12:13], v7 offset0:4 offset1:5
	ds_read2st64_b32 v[14:15], v7 offset0:6 offset1:7
	ds_read2st64_b32 v[16:17], v7 offset0:8 offset1:9
	ds_read2st64_b32 v[18:19], v7 offset0:10 offset1:11
	ds_read2st64_b32 v[20:21], v7 offset0:12 offset1:13
	ds_read2st64_b32 v[22:23], v7 offset0:14 offset1:15
	s_mul_hi_u32 s0, s40, 0x80000001
	s_mul_i32 s1, s0, 2
	s_sub_u32 s1, s40, s1
	s_mul_hi_u32 s2, s1, 0x80000001
	s_mul_i32 s8, s2, 2
	s_sub_u32 s8, s1, s8
	s_lshl_b32 s9, s8, 6
	s_mul_i32 s9, s9, 0x100
	s_mul_i32 s28, s0, 0x8000
	s_add_u32 s9, s9, s28
	s_lshl_b32 s2, s2, 8
	s_add_u32 s9, s9, s2
	s_add_u32 s9, s9, 0x14408000
	s_add_u32 s44, s54, s9
	s_addc_u32 s45, s55, 0
	s_waitcnt lgkmcnt(6)
	v_cvt_pk_bf16_f32 v8, v8, v9
	v_cvt_pk_bf16_f32 v9, v10, v11
	s_waitcnt lgkmcnt(4)
	v_cvt_pk_bf16_f32 v10, v12, v13
	v_cvt_pk_bf16_f32 v11, v14, v15
	s_waitcnt lgkmcnt(2)
	v_cvt_pk_bf16_f32 v12, v16, v17
	v_cvt_pk_bf16_f32 v13, v18, v19
	s_waitcnt lgkmcnt(0)
	v_cvt_pk_bf16_f32 v14, v20, v21
	v_cvt_pk_bf16_f32 v15, v22, v23
	global_store_dwordx4 v5, v[8:11], s[44:45]
	global_store_dwordx4 v5, v[12:15], s[44:45] offset:16
	s_add_u32 s40, s40, 256
	s_add_u32 s41, s41, 0x8000
	s_and_b32 s41, s41, 0x1ffff
	s_cmp_lt_u32 s40, 16
	s_cbranch_scc1 .Lcv_rga_loop
.Lcv_rga_skip:
	s_mov_b32 s40, s60
	s_cmp_lt_u32 s40, 16
	s_cbranch_scc0 .Lcv_rgx_skip
	v_mov_b32_e32 v29, 0x200
	v_mov_b32_e32 v28, 0x100
	v_mad_u32_u24 v0, v30, v29, v31
	v_mad_u32_u24 v5, v26, v28, v27
	v_add_u32_e32 v1, 0x800, v0
	v_add_u32_e32 v2, 0x1000, v0
	v_add_u32_e32 v3, 0x1800, v0
	s_barrier
	s_mov_b32 s41, 0
	s_mov_b32 s47, s40
	s_mov_b32 s48, s46
	s_mul_hi_u32 s0, s47, 0x80000001
	s_mul_i32 s1, s0, 2
	s_sub_u32 s1, s47, s1
	s_mul_hi_u32 s2, s1, 0x80000001
	s_mul_i32 s8, s2, 2
	s_sub_u32 s8, s1, s8
	s_mul_i32 s9, s0, 0x10000
	s_mul_i32 s28, s2, 0x10000
	s_add_u32 s9, s9, s28
	s_lshl_b32 s8, s8, 8
	s_add_u32 s9, s9, s8
	s_add_u32 s42, s88, s9
	s_addc_u32 s43, s89, 0
	s_mov_b32 m0, s48
	s_add_u32 s49, s48, 0x400
	global_load_lds_dwordx4 v0, s[42:43]
	s_mov_b32 m0, s49
	s_add_u32 s49, s48, 0x800
	global_load_lds_dwordx4 v1, s[42:43]
	s_mov_b32 m0, s49
	s_add_u32 s49, s48, 0xc00
	global_load_lds_dwordx4 v2, s[42:43]
	s_mov_b32 m0, s49
	s_nop 0
	global_load_lds_dwordx4 v3, s[42:43]
	global_load_dword v24, v173, s[88:89]
	global_load_dword v24, v173, s[88:89]
	s_add_u32 s47, s40, 256
	s_add_u32 s48, s46, 0x8000
	s_cmp_lt_u32 s47, 16
	s_cbranch_scc0 .Lcv_rgx_pd1
	s_mul_hi_u32 s0, s47, 0x80000001
	s_mul_i32 s1, s0, 2
	s_sub_u32 s1, s47, s1
	s_mul_hi_u32 s2, s1, 0x80000001
	s_mul_i32 s8, s2, 2
	s_sub_u32 s8, s1, s8
	s_mul_i32 s9, s0, 0x10000
	s_mul_i32 s28, s2, 0x10000
	s_add_u32 s9, s9, s28
	s_lshl_b32 s8, s8, 8
	s_add_u32 s9, s9, s8
	s_add_u32 s42, s88, s9
	s_addc_u32 s43, s89, 0
	s_mov_b32 m0, s48
	s_add_u32 s49, s48, 0x400
	global_load_lds_dwordx4 v0, s[42:43]
	s_mov_b32 m0, s49
	s_add_u32 s49, s48, 0x800
	global_load_lds_dwordx4 v1, s[42:43]
	s_mov_b32 m0, s49
	s_add_u32 s49, s48, 0xc00
	global_load_lds_dwordx4 v2, s[42:43]
	s_mov_b32 m0, s49
	s_nop 0
	global_load_lds_dwordx4 v3, s[42:43]
	s_branch .Lcv_rgx_pj1
.Lcv_rgx_pd1:
	global_load_dword v24, v173, s[88:89]
	global_load_dword v24, v173, s[88:89]
	global_load_dword v24, v173, s[88:89]
	global_load_dword v24, v173, s[88:89]
.Lcv_rgx_pj1:
	global_load_dword v24, v173, s[88:89]
	global_load_dword v24, v173, s[88:89]
	s_add_u32 s47, s40, 512
	s_add_u32 s48, s46, 0x10000
	s_cmp_lt_u32 s47, 16
	s_cbranch_scc0 .Lcv_rgx_pd2
	s_mul_hi_u32 s0, s47, 0x80000001
	s_mul_i32 s1, s0, 2
	s_sub_u32 s1, s47, s1
	s_mul_hi_u32 s2, s1, 0x80000001
	s_mul_i32 s8, s2, 2
	s_sub_u32 s8, s1, s8
	s_mul_i32 s9, s0, 0x10000
	s_mul_i32 s28, s2, 0x10000
	s_add_u32 s9, s9, s28
	s_lshl_b32 s8, s8, 8
	s_add_u32 s9, s9, s8
	s_add_u32 s42, s88, s9
	s_addc_u32 s43, s89, 0
	s_mov_b32 m0, s48
	s_add_u32 s49, s48, 0x400
	global_load_lds_dwordx4 v0, s[42:43]
	s_mov_b32 m0, s49
	s_add_u32 s49, s48, 0x800
	global_load_lds_dwordx4 v1, s[42:43]
	s_mov_b32 m0, s49
	s_add_u32 s49, s48, 0xc00
	global_load_lds_dwordx4 v2, s[42:43]
	s_mov_b32 m0, s49
	s_nop 0
	global_load_lds_dwordx4 v3, s[42:43]
	s_branch .Lcv_rgx_pj2

; __device__ __forceinline__ void lds_barrier() { asm volatile("s_waitcnt lgkmcnt(0)" ::: "memory"); __builtin_amdgcn_s_barrier(); asm volatile("" ::: "memory"); }
; #define CVT_LOAD(tile_) do { const int k0_ = ((tile_) / ntn) << 7, n0_ = ((tile_) % ntn) << 6; \
;         _Pragma("unroll") for (int pp = 0; pp < 4; ++pp) pv[pp] = *(const float4*)(src + (size_t)(k0_ + lk + 32 * pp) * N + n0_ + ln4); } while (0)
; __device__ __forceinline__ void convT_job(const float* __restrict__ src, bf16_t* __restrict__ dst, int K, int N, int mode, float* t) {
;     ...
; #pragma unroll 1
;     for (; tile < ntiles; tile += gridDim.x) {
;         const int k0 = (tile / ntn) << 7, n0 = (tile % ntn) << 6;
; #pragma unroll
;         for (int pp = 0; pp < 4; ++pp) { const int k = lk + 32 * pp; t[k * 65 + ln4] = pv[pp].x; t[k * 65 + ln4 + 1] = pv[pp].y; t[k * 65 + ln4 + 2] = pv[pp].z; t[k * 65 + ln4 + 3] = pv[pp].w; }
;         if (tile + (int)gridDim.x < ntiles) CVT_LOAD(tile + (int)gridDim.x);
;         lds_barrier();
.Lcv_rgx_pj2:
	global_load_dword v24, v173, s[88:89]
	global_load_dword v24, v173, s[88:89]
.Lcv_rgx_loop:
	s_waitcnt vmcnt(14)
	s_barrier
	s_add_u32 s47, s40, 768
	s_add_u32 s48, s41, 0x18000
	s_and_b32 s48, s48, 0x1ffff
	s_add_u32 s48, s48, s46
	s_cmp_lt_u32 s47, 16
	s_cbranch_scc0 .Lcv_rgx_ld
	s_mul_hi_u32 s0, s47, 0x80000001
	s_mul_i32 s1, s0, 2
	s_sub_u32 s1, s47, s1
	s_mul_hi_u32 s2, s1, 0x80000001
	s_mul_i32 s8, s2, 2
	s_sub_u32 s8, s1, s8
	s_mul_i32 s9, s0, 0x10000
	s_mul_i32 s28, s2, 0x10000
	s_add_u32 s9, s9, s28
	s_lshl_b32 s8, s8, 8
	s_add_u32 s9, s9, s8
	s_add_u32 s42, s88, s9
	s_addc_u32 s43, s89, 0
	s_mov_b32 m0, s48
	s_add_u32 s49, s48, 0x400
	global_load_lds_dwordx4 v0, s[42:43]
	s_mov_b32 m0, s49
	s_add_u32 s49, s48, 0x800
	global_load_lds_dwordx4 v1, s[42:43]
	s_mov_b32 m0, s49
	s_add_u32 s49, s48, 0xc00
	global_load_lds_dwordx4 v2, s[42:43]
	s_mov_b32 m0, s49
	s_nop 0
	global_load_lds_dwordx4 v3, s[42:43]
	s_branch .Lcv_rgx_lj

; __device__ __forceinline__ unsigned cvt_pk_bf16(float lo, float hi) { unsigned r; asm volatile("v_cvt_pk_bf16_f32 %0, %1, %2" : "=v"(r) : "v"(lo), "v"(hi)); return r; }
; __device__ __forceinline__ void lds_barrier() { asm volatile("s_waitcnt lgkmcnt(0)" ::: "memory"); __builtin_amdgcn_s_barrier(); asm volatile("" ::: "memory"); }
; __device__ __forceinline__ void convT_job(const float* __restrict__ src, bf16_t* __restrict__ dst, int K, int N, int mode, float* t) {
;     ...
;         const int n = tid >> 3, k16 = (tid & 7) * 16;
;         float v[16];
; #pragma unroll
;         for (int j = 0; j < 16; ++j) v[j] = t[(k16 + j) * 65 + n];
;         const int nn = n0 + n;
;         const int row = mode == 0 ? nn : (256 * (nn >> 7) + (nn & 127) + (mode == 2 ? 128 : 0));
;         u32x4 w0, w1; w0.x = cvt_pk_bf16(v[0], v[1]); w0.y = cvt_pk_bf16(v[2], v[3]); w0.z = cvt_pk_bf16(v[4], v[5]); w0.w = cvt_pk_bf16(v[6], v[7]);
;         w1.x = cvt_pk_bf16(v[8], v[9]); w1.y = cvt_pk_bf16(v[10], v[11]); w1.z = cvt_pk_bf16(v[12], v[13]); w1.w = cvt_pk_bf16(v[14], v[15]);
;         bf16_t* d = dst + (size_t)row * K + k0 + k16;
;         *(u32x4*)d = w0; *(u32x4*)(d + 8) = w1;
;         lds_barrier();
;     }
.Lcv_rgx_lj:
	v_add_u32_e32 v7, s41, v4
	ds_read2st64_b32 v[8:9], v7 offset0:0 offset1:1
	ds_read2st64_b32 v[10:11], v7 offset0:2 offset1:3
	ds_read2st64_b32 v[12:13], v7 offset0:4 offset1:5
	ds_read2st64_b32 v[14:15], v7 offset0:6 offset1:7
	ds_read2st64_b32 v[16:17], v7 offset0:8 offset1:9
	ds_read2st64_b32 v[18:19], v7 offset0:10 offset1:11
	ds_read2st64_b32 v[20:21], v7 offset0:12 offset1:13
	ds_read2st64_b32 v[22:23], v7 offset0:14 offset1:15
	s_mul_hi_u32 s0, s40, 0x80000001
	s_mul_i32 s1, s0, 2
	s_sub_u32 s1, s40, s1
	s_mul_hi_u32 s2, s1, 0x80000001
	s_mul_i32 s8, s2, 2
	s_sub_u32 s8, s1, s8
	s_lshl_b32 s9, s8, 6
	s_mul_i32 s9, s9, 0x100
	s_mul_i32 s28, s0, 0x8000
	s_add_u32 s9, s9, s28
	s_lshl_b32 s2, s2, 8
	s_add_u32 s9, s9, s2
	s_add_u32 s9, s9, 0x14448000
	s_add_u32 s44, s54, s9
	s_addc_u32 s45, s55, 0
	s_waitcnt lgkmcnt(6)
	v_cvt_pk_bf16_f32 v8, v8, v9
	v_cvt_pk_bf16_f32 v9, v10, v11
	s_waitcnt lgkmcnt(4)
	v_cvt_pk_bf16_f32 v10, v12, v13
	v_cvt_pk_bf16_f32 v11, v14, v15
	s_waitcnt lgkmcnt(2)
	v_cvt_pk_bf16_f32 v12, v16, v17
	v_cvt_pk_bf16_f32 v13, v18, v19
	s_waitcnt lgkmcnt(0)
	v_cvt_pk_bf16_f32 v14, v20, v21
	v_cvt_pk_bf16_f32 v15, v22, v23
	global_store_dwordx4 v5, v[8:11], s[44:45]
	global_store_dwordx4 v5, v[12:15], s[44:45] offset:16
	s_add_u32 s40, s40, 256
	s_add_u32 s41, s41, 0x8000
	s_and_b32 s41, s41, 0x1ffff
	s_cmp_lt_u32 s40, 16
	s_cbranch_scc1 .Lcv_rgx_loop
.Lcv_rgx_skip:
	s_barrier
	s_branch .LBB0_679
